# XCD-aware tile order extended: up GEMMs and diff in-proj in 8x8 row/col windows per XCD, both transposed-V GEMMs with token-tile sharers on one XCD
# speedup vs baseline: 1.1911x; 1.0049x over previous
; template <class Epi>
; __device__ __forceinline__ void gemm_tile(const bf16_t* __restrict__ A, const bf16_t* __restrict__ Bt, int K, int row0, int col0, const Epi& epi, char* smem,
;                                           bool prefetched, bool nvalid, int nrow0, int ncol0) {
;     ...
;     const bf16_t* pA = A + (size_t)row0 * K;
;     const bf16_t* pB = Bt + (size_t)col0 * K;
;     ...
;     int offA[4][2], offB[4][2];
; #pragma unroll
;     for (int m = 0; m < 4; ++m)
; #pragma unroll
;         for (int ks = 0; ks < 2; ++ks) { const int cx = ((ks * 4 + fq) ^ ((fr >> 1) & 7)) * 16;
;             offA[m][ks] = (wr * 64 + m * 16 + fr) * 128 + cx;
;             offB[m][ks] = TILE_B + (wc * 64 + (m >> 1) * 32 + 8 * (fr >> 2) + 4 * (m & 1) + (fr & 3)) * 128 + cx; }
;     if (prefetched) {
;         if (Epi::STAGED) asm volatile("s_waitcnt vmcnt(8)" ::: "memory");
;         else asm volatile("s_waitcnt vmcnt(0)" ::: "memory");
;     } else {
;         GLDS_STAGE(0, pA, pB, 0);
;         asm volatile("s_waitcnt vmcnt(0)" ::: "memory");
; template <class E1, class E2>
; __device__ __forceinline__ void gemm_phase2(const bf16_t* A1, const bf16_t* B1, int M1, int N1, const E1& e1,
;                                             const bf16_t* A2, const bf16_t* B2, int M2, int N2, const E2& e2, int K, char* smem) {
;     ...
;     for (int i = (blockIdx.x + (G >> 1)) % G; i < nt2; i += G) {
;         const int j = i + G; const bool nv = j < nt2;
;         gemm_tile(A2, B2, K, (i % nM2) << 7, (i / nM2) << 7, e2, smem, pre, nv, (j % nM2) << 7, (j / nM2) << 7);
.LBB0_192:
	s_and_b32 s2, s14, 7
	s_lshl_b32 s2, s2, 2
	s_bfe_u32 s3, s14, 0x20003
	s_or_b32 s2, s2, s3
	s_and_b32 s3, s14, 0xffffffe0
	s_or_b32 s3, s2, s3
	s_ashr_i32 s0, s3, 31
	s_lshr_b32 s0, s0, 30
	s_add_i32 s0, s3, s0
	s_and_b32 s1, s0, 0x1fffffc
	s_sub_i32 s1, s3, s1
	s_lshl_b32 s0, s0, 5
	s_lshl_b32 s2, s1, 7
	s_and_b32 s0, s0, 0xffffff80
	s_ashr_i32 s3, s2, 31
	s_ashr_i32 s1, s0, 31
	s_lshl_b64 s[4:5], s[2:3], 11
	s_lshl_b64 s[6:7], s[0:1], 11
	s_mov_b64 s[10:11], -1
	s_and_b64 vcc, exec, s[8:9]
	s_cbranch_vccnz .LBB0_194
	s_add_u32 s8, s12, s4
	s_addc_u32 s9, s13, s5
	v_readlane_b32 s1, v245, 53
	s_add_u32 s10, s1, s6
	v_readlane_b32 s1, v245, 54
	s_addc_u32 s11, s1, s7
	v_readfirstlane_b32 s1, v149
	s_mov_b32 m0, s1
	v_readfirstlane_b32 s1, v131
	global_load_lds_dwordx4 v163, s[8:9]
	v_lshl_add_u64 v[0:1], v[64:65], 1, s[10:11]
	s_mov_b32 m0, s1
	v_readfirstlane_b32 s1, v139
	global_load_lds_dwordx4 v[0:1], off
	s_mov_b32 m0, s1
	v_readfirstlane_b32 s1, v140
	global_load_lds_dwordx4 v164, s[8:9]
	v_lshl_add_u64 v[0:1], v[66:67], 1, s[10:11]
	s_mov_b32 m0, s1
	v_readfirstlane_b32 s1, v141
	global_load_lds_dwordx4 v[0:1], off
	s_mov_b32 m0, s1
	v_readfirstlane_b32 s1, v142
	global_load_lds_dwordx4 v165, s[8:9]
	v_lshl_add_u64 v[0:1], v[68:69], 1, s[10:11]
	s_mov_b32 m0, s1
	v_readfirstlane_b32 s1, v143
	global_load_lds_dwordx4 v[0:1], off
	s_mov_b32 m0, s1
	v_readfirstlane_b32 s1, v144
	global_load_lds_dwordx4 v166, s[8:9]
	v_lshl_add_u64 v[0:1], v[70:71], 1, s[10:11]
	s_mov_b32 m0, s1
	s_mov_b64 s[10:11], 0
	global_load_lds_dwordx4 v[0:1], off
	s_waitcnt vmcnt(0)

; __device__ __forceinline__ f32x4 mfma16(bf16x8 a, bf16x8 b, f32x4 c) { return __builtin_amdgcn_mfma_f32_16x16x32_bf16(a, b, c, 0, 0, 0); }
; template <class Epi>
; __device__ __forceinline__ void gemm_tile(const bf16_t* __restrict__ A, const bf16_t* __restrict__ Bt, int K, int row0, int col0, const Epi& epi, char* smem,
;                                           bool prefetched, bool nvalid, int nrow0, int ncol0) {
;     ...
; #pragma unroll
;         for (int ks = 0; ks < 2; ++ks) {
;             bf16x8 a[4], b[4];
; #pragma unroll
;             for (int m = 0; m < 4; ++m) a[m] = *(const bf16x8*)(cb + offA[m][ks]);
; #pragma unroll
;             for (int n = 0; n < 4; ++n) b[n] = *(const bf16x8*)(cb + offB[n][ks]);
; #pragma unroll
;             for (int m = 0; m < 4; ++m)
; #pragma unroll
;                 for (int n = 0; n < 4; ++n) acc[m][n] = mfma16(b[n], a[m], acc[m][n]);
;         }
;         asm volatile("s_waitcnt vmcnt(0)" ::: "memory");
;         __syncthreads();
;     }
;     if (nvalid) { const bf16_t* qA = A + (size_t)nrow0 * K; const bf16_t* qB = Bt + (size_t)ncol0 * K; GLDS_STAGE(0, qA, qB, 0); }
; template <class E1, class E2>
; __device__ __forceinline__ void gemm_phase2(const bf16_t* A1, const bf16_t* B1, int M1, int N1, const E1& e1,
;                                             const bf16_t* A2, const bf16_t* B2, int M2, int N2, const E2& e2, int K, char* smem) {
;     ...
;     for (int i = (blockIdx.x + (G >> 1)) % G; i < nt2; i += G) {
;         const int j = i + G; const bool nv = j < nt2;
;         gemm_tile(A2, B2, K, (i % nM2) << 7, (i / nM2) << 7, e2, smem, pre, nv, (j % nM2) << 7, (j / nM2) << 7);
.Lgk_tail_197:
	v_mfma_f32_16x16x32_bf16 v[32:35], v[172:175], v[196:199], v[32:35]
	v_mfma_f32_16x16x32_bf16 v[36:39], v[176:179], v[196:199], v[36:39]
	v_mfma_f32_16x16x32_bf16 v[40:43], v[180:183], v[196:199], v[40:43]
	v_mfma_f32_16x16x32_bf16 v[44:47], v[184:187], v[196:199], v[44:47]
	v_mfma_f32_16x16x32_bf16 v[48:51], v[172:175], v[246:249], v[48:51]
	v_mfma_f32_16x16x32_bf16 v[52:55], v[176:179], v[246:249], v[52:55]
	v_mfma_f32_16x16x32_bf16 v[56:59], v[180:183], v[246:249], v[56:59]
	v_mfma_f32_16x16x32_bf16 v[60:63], v[184:187], v[246:249], v[60:63]
	ds_read_b128 v[106:109], v130 offset:49152
	ds_read_b128 v[118:121], v117 offset:32768
	ds_read_b128 v[122:125], v130 offset:49664
	ds_read_b128 v[168:171], v130 offset:53248
	ds_read_b128 v[172:175], v130 offset:53760
	s_add_i32 s14, s14, s58
	s_waitcnt lgkmcnt(3)
	v_mfma_f32_16x16x32_bf16 v[0:3], v[106:109], v[118:121], v[0:3]
	s_cmpk_gt_i32 s14, 0x3ff
	s_cselect_b64 s[4:5], -1, 0
	s_cmpk_lt_i32 s14, 0x400
	s_waitcnt lgkmcnt(2)
	v_mfma_f32_16x16x32_bf16 v[4:7], v[122:125], v[118:121], v[4:7]
	ds_read_b128 v[188:191], v129 offset:49152
	ds_read_b128 v[192:195], v129 offset:53248
	ds_read_b128 v[196:199], v129 offset:53760
	s_waitcnt lgkmcnt(4)
	v_mfma_f32_16x16x32_bf16 v[8:11], v[168:171], v[118:121], v[8:11]
	s_waitcnt lgkmcnt(3)
	v_mfma_f32_16x16x32_bf16 v[12:15], v[172:175], v[118:121], v[12:15]
	ds_read_b128 v[118:121], v117 offset:34816
	s_waitcnt lgkmcnt(0)
	v_mfma_f32_16x16x32_bf16 v[16:19], v[106:109], v[118:121], v[16:19]
	v_mfma_f32_16x16x32_bf16 v[20:23], v[122:125], v[118:121], v[20:23]
	v_mfma_f32_16x16x32_bf16 v[24:27], v[168:171], v[118:121], v[24:27]
	v_mfma_f32_16x16x32_bf16 v[28:31], v[172:175], v[118:121], v[28:31]
	ds_read_b128 v[118:121], v117 offset:36864
	s_waitcnt lgkmcnt(0)
	v_mfma_f32_16x16x32_bf16 v[176:179], v[106:109], v[118:121], v[32:35]
	s_nop 2
	ds_read_b128 v[32:35], v117 offset:38912
	v_mfma_f32_16x16x32_bf16 v[180:183], v[122:125], v[118:121], v[36:39]
	v_mfma_f32_16x16x32_bf16 v[184:187], v[168:171], v[118:121], v[40:43]
	v_mfma_f32_16x16x32_bf16 v[118:121], v[172:175], v[118:121], v[44:47]
	s_waitcnt lgkmcnt(0)
	v_mfma_f32_16x16x32_bf16 v[106:109], v[106:109], v[32:35], v[48:51]
	v_mfma_f32_16x16x32_bf16 v[122:125], v[122:125], v[32:35], v[52:55]
	v_mfma_f32_16x16x32_bf16 v[168:171], v[168:171], v[32:35], v[56:59]
	v_mfma_f32_16x16x32_bf16 v[172:175], v[172:175], v[32:35], v[60:63]
	ds_read_b128 v[32:35], v128 offset:32768
	s_waitcnt lgkmcnt(0)
	v_mfma_f32_16x16x32_bf16 v[56:59], v[188:191], v[32:35], v[0:3]
	s_nop 2
	ds_read_b128 v[0:3], v129 offset:49664
	s_waitcnt lgkmcnt(0)
	v_mfma_f32_16x16x32_bf16 v[60:63], v[0:3], v[32:35], v[4:7]
	s_nop 2
	ds_read_b128 v[4:7], v128 offset:34816
	v_mfma_f32_16x16x32_bf16 v[48:51], v[192:195], v[32:35], v[8:11]
	v_mfma_f32_16x16x32_bf16 v[52:55], v[196:199], v[32:35], v[12:15]
	s_nop 2
	ds_read_b128 v[12:15], v128 offset:38912
	s_waitcnt lgkmcnt(1)
	v_mfma_f32_16x16x32_bf16 v[44:47], v[188:191], v[4:7], v[16:19]
	v_mfma_f32_16x16x32_bf16 v[40:43], v[0:3], v[4:7], v[20:23]
	v_mfma_f32_16x16x32_bf16 v[36:39], v[192:195], v[4:7], v[24:27]
	v_mfma_f32_16x16x32_bf16 v[32:35], v[196:199], v[4:7], v[28:31]
	ds_read_b128 v[4:7], v128 offset:36864
	s_waitcnt vmcnt(0)
	s_waitcnt lgkmcnt(0)
	v_mfma_f32_16x16x32_bf16 v[28:31], v[188:191], v[4:7], v[176:179]
	s_barrier
	v_mfma_f32_16x16x32_bf16 v[24:27], v[0:3], v[4:7], v[180:183]
	v_mfma_f32_16x16x32_bf16 v[20:23], v[192:195], v[4:7], v[184:187]
	v_mfma_f32_16x16x32_bf16 v[16:19], v[196:199], v[4:7], v[118:121]
	v_mfma_f32_16x16x32_bf16 v[4:7], v[188:191], v[12:15], v[106:109]
	v_mfma_f32_16x16x32_bf16 v[8:11], v[0:3], v[12:15], v[122:125]
	v_mfma_f32_16x16x32_bf16 v[0:3], v[192:195], v[12:15], v[168:171]
	v_mfma_f32_16x16x32_bf16 v[12:15], v[196:199], v[12:15], v[172:175]
	s_cbranch_scc0 .LBB0_191
	s_and_b32 s8, s14, 7
	s_lshl_b32 s8, s8, 2
	s_bfe_u32 s9, s14, 0x20003
	s_or_b32 s8, s8, s9
	s_and_b32 s9, s14, 0xffffffe0
	s_or_b32 s9, s8, s9
	s_ashr_i32 s1, s9, 31
	s_lshr_b32 s1, s1, 30
	s_add_i32 s1, s9, s1
	s_and_b32 s6, s1, 0x1fffffc
	s_sub_i32 s6, s9, s6
	s_lshl_b32 s6, s6, 7
	s_lshl_b32 s1, s1, 5
	s_ashr_i32 s7, s6, 31
	s_and_b32 s8, s1, 0xffffff80
	s_lshl_b64 s[6:7], s[6:7], 11
	s_add_u32 s6, s12, s6
	s_addc_u32 s7, s13, s7
	s_ashr_i32 s9, s8, 31
	s_lshl_b64 s[8:9], s[8:9], 11
	v_readlane_b32 s1, v245, 53
	s_add_u32 s8, s1, s8
	v_readlane_b32 s1, v245, 54
	s_addc_u32 s9, s1, s9
	v_readfirstlane_b32 s1, v149
	s_mov_b32 m0, s1
	v_readfirstlane_b32 s1, v131
	global_load_lds_dwordx4 v163, s[6:7]
	v_lshl_add_u64 v[106:107], v[64:65], 1, s[8:9]
	s_mov_b32 m0, s1
	v_readfirstlane_b32 s1, v139
	global_load_lds_dwordx4 v[106:107], off
	s_mov_b32 m0, s1
	v_readfirstlane_b32 s1, v140
	global_load_lds_dwordx4 v164, s[6:7]
	v_lshl_add_u64 v[106:107], v[66:67], 1, s[8:9]
	s_mov_b32 m0, s1
	v_readfirstlane_b32 s1, v141
	global_load_lds_dwordx4 v[106:107], off
	s_mov_b32 m0, s1
	v_readfirstlane_b32 s1, v142
	global_load_lds_dwordx4 v165, s[6:7]
	v_lshl_add_u64 v[106:107], v[68:69], 1, s[8:9]
	s_mov_b32 m0, s1
	v_readfirstlane_b32 s1, v143
	global_load_lds_dwordx4 v[106:107], off
	s_mov_b32 m0, s1
	v_readfirstlane_b32 s1, v144
	global_load_lds_dwordx4 v166, s[6:7]
	v_lshl_add_u64 v[106:107], v[70:71], 1, s[8:9]
	s_mov_b32 m0, s1
	s_nop 0
	global_load_lds_dwordx4 v[106:107], off
	s_branch .LBB0_191

; template <class Epi>
; __device__ __forceinline__ void gemm_tile(const bf16_t* __restrict__ A, const bf16_t* __restrict__ Bt, int K, int row0, int col0, const Epi& epi, char* smem,
;                                           bool prefetched, bool nvalid, int nrow0, int ncol0) {
;     ...
;     const bf16_t* pA = A + (size_t)row0 * K;
;     const bf16_t* pB = Bt + (size_t)col0 * K;
;     ...
;     int offA[4][2], offB[4][2];
; #pragma unroll
;     for (int m = 0; m < 4; ++m)
; #pragma unroll
;         for (int ks = 0; ks < 2; ++ks) { const int cx = ((ks * 4 + fq) ^ ((fr >> 1) & 7)) * 16;
;             offA[m][ks] = (wr * 64 + m * 16 + fr) * 128 + cx;
;             offB[m][ks] = TILE_B + (wc * 64 + (m >> 1) * 32 + 8 * (fr >> 2) + 4 * (m & 1) + (fr & 3)) * 128 + cx; }
;     if (prefetched) {
;         if (Epi::STAGED) asm volatile("s_waitcnt vmcnt(8)" ::: "memory");
;         else asm volatile("s_waitcnt vmcnt(0)" ::: "memory");
;     } else {
;         GLDS_STAGE(0, pA, pB, 0);
;         asm volatile("s_waitcnt vmcnt(0)" ::: "memory");
; template <class Epi>
; __device__ __forceinline__ void gemm_phase(const bf16_t* A, const bf16_t* Bt, int M, int N, int K, const Epi& epi, char* smem) {
;     ...
;     for (int i = blockIdx.x; i < ntiles; i += G) {
;         const int j = i + G; const bool nv = j < ntiles;
;         gemm_tile(A, Bt, K, (i / nN) << 7, (i % nN) << 7, epi, smem, pre, nv, (j / nN) << 7, (j % nN) << 7);
.LBB0_558:
	s_and_b32 s4, s16, 7
	s_lshl_b32 s4, s4, 3
	s_bfe_u32 s5, s16, 0x30006
	s_or_b32 s4, s4, s5
	s_lshr_b32 s5, s16, 11
	s_lshl_b32 s5, s5, 6
	s_or_b32 s4, s4, s5
	s_lshl_b32 s4, s4, 5
	s_bfe_u32 s5, s16, 0x30003
	s_or_b32 s4, s4, s5
	s_bfe_u32 s5, s16, 0x20009
	s_lshl_b32 s5, s5, 3
	s_or_b32 s5, s4, s5
	s_ashr_i32 s0, s5, 31
	s_lshr_b32 s0, s0, 27
	s_add_i32 s1, s5, s0
	s_lshl_b32 s0, s1, 2
	s_and_b32 s1, s1, 0x1ffffe0
	s_sub_i32 s1, s5, s1
	s_and_b32 s0, s0, 0xffffff80
	s_lshl_b32 s4, s1, 7
	s_ashr_i32 s1, s0, 31
	s_ashr_i32 s5, s4, 31
	s_lshl_b64 s[6:7], s[0:1], 11
	s_lshl_b64 s[8:9], s[4:5], 11
	s_mov_b64 s[12:13], -1
	s_and_b64 vcc, exec, s[10:11]
	s_cbranch_vccnz .LBB0_560
	v_readlane_b32 s10, v245, 53
	s_add_u32 s10, s10, s6
	v_readlane_b32 s11, v245, 54
	s_addc_u32 s11, s11, s7
	s_add_u32 s12, s14, s8
	v_readfirstlane_b32 s17, v149
	s_addc_u32 s13, s15, s9
	s_mov_b32 m0, s17
	v_readfirstlane_b32 s17, v143
	global_load_lds_dwordx4 v168, s[10:11]
	v_lshl_add_u64 v[0:1], v[64:65], 1, s[12:13]
	s_mov_b32 m0, s17
	v_readfirstlane_b32 s17, v144
	global_load_lds_dwordx4 v[0:1], off
	s_mov_b32 m0, s17
	v_readfirstlane_b32 s17, v145
	global_load_lds_dwordx4 v169, s[10:11]
	v_lshl_add_u64 v[0:1], v[66:67], 1, s[12:13]
	s_mov_b32 m0, s17
	v_readfirstlane_b32 s17, v162
	global_load_lds_dwordx4 v[0:1], off
	s_mov_b32 m0, s17
	v_readfirstlane_b32 s17, v163
	global_load_lds_dwordx4 v170, s[10:11]
	v_lshl_add_u64 v[0:1], v[68:69], 1, s[12:13]
	s_mov_b32 m0, s17
	v_readfirstlane_b32 s17, v164
	global_load_lds_dwordx4 v[0:1], off
	s_mov_b32 m0, s17
	v_lshl_add_u64 v[0:1], v[70:71], 1, s[12:13]
	global_load_lds_dwordx4 v171, s[10:11]
	v_readfirstlane_b32 s10, v165
	s_mov_b32 m0, s10
	s_mov_b64 s[12:13], 0
	global_load_lds_dwordx4 v[0:1], off
	s_waitcnt vmcnt(0)

; __device__ __forceinline__ f32x4 mfma16(bf16x8 a, bf16x8 b, f32x4 c) { return __builtin_amdgcn_mfma_f32_16x16x32_bf16(a, b, c, 0, 0, 0); }
; template <class Epi>
; __device__ __forceinline__ void gemm_tile(const bf16_t* __restrict__ A, const bf16_t* __restrict__ Bt, int K, int row0, int col0, const Epi& epi, char* smem,
;                                           bool prefetched, bool nvalid, int nrow0, int ncol0) {
;     ...
; #pragma unroll
;         for (int ks = 0; ks < 2; ++ks) {
;             bf16x8 a[4], b[4];
; #pragma unroll
;             for (int m = 0; m < 4; ++m) a[m] = *(const bf16x8*)(cb + offA[m][ks]);
; #pragma unroll
;             for (int n = 0; n < 4; ++n) b[n] = *(const bf16x8*)(cb + offB[n][ks]);
; #pragma unroll
;             for (int m = 0; m < 4; ++m)
; #pragma unroll
;                 for (int n = 0; n < 4; ++n) acc[m][n] = mfma16(b[n], a[m], acc[m][n]);
;         }
;         asm volatile("s_waitcnt vmcnt(0)" ::: "memory");
;         __syncthreads();
;     }
;     if (nvalid) { const bf16_t* qA = A + (size_t)nrow0 * K; const bf16_t* qB = Bt + (size_t)ncol0 * K; GLDS_STAGE(0, qA, qB, 0); }
; template <class Epi>
; __device__ __forceinline__ void gemm_phase(const bf16_t* A, const bf16_t* Bt, int M, int N, int K, const Epi& epi, char* smem) {
;     ...
;     for (int i = blockIdx.x; i < ntiles; i += G) {
;         const int j = i + G; const bool nv = j < ntiles;
;         gemm_tile(A, Bt, K, (i / nN) << 7, (i % nN) << 7, epi, smem, pre, nv, (j / nN) << 7, (j % nN) << 7);
.Lgk_tail_563:
	v_mfma_f32_16x16x32_bf16 v[32:35], v[176:179], v[246:249], v[32:35]
	v_mfma_f32_16x16x32_bf16 v[36:39], v[180:183], v[246:249], v[36:39]
	v_mfma_f32_16x16x32_bf16 v[40:43], v[184:187], v[246:249], v[40:43]
	v_mfma_f32_16x16x32_bf16 v[44:47], v[188:191], v[246:249], v[44:47]
	v_mfma_f32_16x16x32_bf16 v[48:51], v[176:179], v[250:253], v[48:51]
	v_mfma_f32_16x16x32_bf16 v[52:55], v[180:183], v[250:253], v[52:55]
	v_mfma_f32_16x16x32_bf16 v[56:59], v[184:187], v[250:253], v[56:59]
	v_mfma_f32_16x16x32_bf16 v[60:63], v[188:191], v[250:253], v[60:63]
	ds_read_b128 v[118:121], v142 offset:49152
	ds_read_b128 v[122:125], v85 offset:32768
	ds_read_b128 v[126:129], v142 offset:49664
	ds_read_b128 v[172:175], v142 offset:53248
	ds_read_b128 v[176:179], v142 offset:53760
	s_add_i32 s16, s16, s58
	s_waitcnt lgkmcnt(3)
	v_mfma_f32_16x16x32_bf16 v[0:3], v[118:121], v[122:125], v[0:3]
	s_cmpk_gt_i32 s16, 0x1fff
	s_cselect_b64 s[6:7], -1, 0
	s_cmpk_lt_i32 s16, 0x2000
	s_waitcnt lgkmcnt(2)
	v_mfma_f32_16x16x32_bf16 v[4:7], v[126:129], v[122:125], v[4:7]
	ds_read_b128 v[192:195], v141 offset:49152
	ds_read_b128 v[196:199], v141 offset:53760
	s_waitcnt lgkmcnt(3)
	v_mfma_f32_16x16x32_bf16 v[8:11], v[172:175], v[122:125], v[8:11]
	s_waitcnt lgkmcnt(2)
	v_mfma_f32_16x16x32_bf16 v[12:15], v[176:179], v[122:125], v[12:15]
	ds_read_b128 v[122:125], v85 offset:34816
	s_waitcnt lgkmcnt(0)
	v_mfma_f32_16x16x32_bf16 v[16:19], v[118:121], v[122:125], v[16:19]
	v_mfma_f32_16x16x32_bf16 v[20:23], v[126:129], v[122:125], v[20:23]
	v_mfma_f32_16x16x32_bf16 v[24:27], v[172:175], v[122:125], v[24:27]
	v_mfma_f32_16x16x32_bf16 v[28:31], v[176:179], v[122:125], v[28:31]
	ds_read_b128 v[122:125], v85 offset:36864
	s_waitcnt lgkmcnt(0)
	v_mfma_f32_16x16x32_bf16 v[180:183], v[118:121], v[122:125], v[32:35]
	s_nop 2
	ds_read_b128 v[32:35], v85 offset:38912
	v_mfma_f32_16x16x32_bf16 v[184:187], v[126:129], v[122:125], v[36:39]
	v_mfma_f32_16x16x32_bf16 v[188:191], v[172:175], v[122:125], v[40:43]
	v_mfma_f32_16x16x32_bf16 v[122:125], v[176:179], v[122:125], v[44:47]
	s_waitcnt lgkmcnt(0)
	v_mfma_f32_16x16x32_bf16 v[118:121], v[118:121], v[32:35], v[48:51]
	v_mfma_f32_16x16x32_bf16 v[126:129], v[126:129], v[32:35], v[52:55]
	v_mfma_f32_16x16x32_bf16 v[172:175], v[172:175], v[32:35], v[56:59]
	v_mfma_f32_16x16x32_bf16 v[176:179], v[176:179], v[32:35], v[60:63]
	ds_read_b128 v[32:35], v87 offset:32768
	s_waitcnt lgkmcnt(0)
	v_mfma_f32_16x16x32_bf16 v[56:59], v[192:195], v[32:35], v[0:3]
	s_nop 2
	ds_read_b128 v[0:3], v141 offset:49664
	s_waitcnt lgkmcnt(0)
	v_mfma_f32_16x16x32_bf16 v[60:63], v[0:3], v[32:35], v[4:7]
	s_nop 2
	ds_read_b128 v[4:7], v141 offset:53248
	s_waitcnt lgkmcnt(0)
	v_mfma_f32_16x16x32_bf16 v[48:51], v[4:7], v[32:35], v[8:11]
	s_nop 2
	ds_read_b128 v[8:11], v87 offset:34816
	v_mfma_f32_16x16x32_bf16 v[52:55], v[196:199], v[32:35], v[12:15]
	s_waitcnt lgkmcnt(0)
	v_mfma_f32_16x16x32_bf16 v[44:47], v[192:195], v[8:11], v[16:19]
	v_mfma_f32_16x16x32_bf16 v[40:43], v[0:3], v[8:11], v[20:23]
	v_mfma_f32_16x16x32_bf16 v[36:39], v[4:7], v[8:11], v[24:27]
	v_mfma_f32_16x16x32_bf16 v[32:35], v[196:199], v[8:11], v[28:31]
	ds_read_b128 v[8:11], v87 offset:36864
	s_waitcnt lgkmcnt(0)
	v_mfma_f32_16x16x32_bf16 v[16:19], v[196:199], v[8:11], v[122:125]
	s_nop 2
	ds_read_b128 v[122:125], v87 offset:38912
	s_waitcnt vmcnt(0)
	v_mfma_f32_16x16x32_bf16 v[28:31], v[192:195], v[8:11], v[180:183]
	s_waitcnt lgkmcnt(0)
	s_barrier
	v_mfma_f32_16x16x32_bf16 v[24:27], v[0:3], v[8:11], v[184:187]
	v_mfma_f32_16x16x32_bf16 v[20:23], v[4:7], v[8:11], v[188:191]
	v_mfma_f32_16x16x32_bf16 v[8:11], v[192:195], v[122:125], v[118:121]
	v_mfma_f32_16x16x32_bf16 v[12:15], v[0:3], v[122:125], v[126:129]
	v_mfma_f32_16x16x32_bf16 v[0:3], v[4:7], v[122:125], v[172:175]
	v_mfma_f32_16x16x32_bf16 v[4:7], v[196:199], v[122:125], v[176:179]
	s_cbranch_scc0 .LBB0_557
	s_and_b32 s10, s16, 7
	s_lshl_b32 s10, s10, 3
	s_bfe_u32 s11, s16, 0x30006
	s_or_b32 s10, s10, s11
	s_lshr_b32 s11, s16, 11
	s_lshl_b32 s11, s11, 6
	s_or_b32 s10, s10, s11
	s_lshl_b32 s10, s10, 5
	s_bfe_u32 s11, s16, 0x30003
	s_or_b32 s10, s10, s11
	s_bfe_u32 s11, s16, 0x20009
	s_lshl_b32 s11, s11, 3
	s_or_b32 s11, s10, s11
	s_ashr_i32 s8, s11, 31
	s_lshr_b32 s8, s8, 27
	s_add_i32 s9, s11, s8
	s_lshl_b32 s8, s9, 2
	s_and_b32 s9, s9, 0x1ffffe0
	s_and_b32 s8, s8, 0xffffff80
	s_sub_i32 s9, s11, s9
	s_lshl_b32 s10, s9, 7
	s_ashr_i32 s9, s8, 31
	s_lshl_b64 s[8:9], s[8:9], 11
	v_readlane_b32 s11, v245, 53
	s_add_u32 s8, s11, s8
	v_readlane_b32 s11, v245, 54
	s_addc_u32 s9, s11, s9
	s_ashr_i32 s11, s10, 31
	s_lshl_b64 s[10:11], s[10:11], 11
	s_add_u32 s10, s14, s10
	v_readfirstlane_b32 s12, v149
	s_addc_u32 s11, s15, s11
	s_mov_b32 m0, s12
	v_readfirstlane_b32 s12, v143
	global_load_lds_dwordx4 v168, s[8:9]
	v_lshl_add_u64 v[110:111], v[64:65], 1, s[10:11]
	s_mov_b32 m0, s12
	v_readfirstlane_b32 s12, v144
	global_load_lds_dwordx4 v[110:111], off
	s_mov_b32 m0, s12
	v_readfirstlane_b32 s12, v145
	global_load_lds_dwordx4 v169, s[8:9]
	v_lshl_add_u64 v[110:111], v[66:67], 1, s[10:11]
	s_mov_b32 m0, s12
	v_readfirstlane_b32 s12, v162
	global_load_lds_dwordx4 v[110:111], off
	s_mov_b32 m0, s12
	v_readfirstlane_b32 s12, v163
	global_load_lds_dwordx4 v170, s[8:9]
	v_lshl_add_u64 v[110:111], v[68:69], 1, s[10:11]
	s_mov_b32 m0, s12
	v_readfirstlane_b32 s12, v164
	global_load_lds_dwordx4 v[110:111], off
	s_mov_b32 m0, s12
	v_lshl_add_u64 v[110:111], v[70:71], 1, s[10:11]
	global_load_lds_dwordx4 v171, s[8:9]
	v_readfirstlane_b32 s8, v165
	s_mov_b32 m0, s8
	s_nop 0
	global_load_lds_dwordx4 v[110:111], off
	s_branch .LBB0_557

; template <class Epi>
; __device__ __forceinline__ void gemm_tile(const bf16_t* __restrict__ A, const bf16_t* __restrict__ Bt, int K, int row0, int col0, const Epi& epi, char* smem,
;                                           bool prefetched, bool nvalid, int nrow0, int ncol0) {
;     ...
;     const bf16_t* pA = A + (size_t)row0 * K;
;     const bf16_t* pB = Bt + (size_t)col0 * K;
;     ...
;     int offA[4][2], offB[4][2];
; #pragma unroll
;     for (int m = 0; m < 4; ++m)
; #pragma unroll
;         for (int ks = 0; ks < 2; ++ks) { const int cx = ((ks * 4 + fq) ^ ((fr >> 1) & 7)) * 16;
;             offA[m][ks] = (wr * 64 + m * 16 + fr) * 128 + cx;
;             offB[m][ks] = TILE_B + (wc * 64 + (m >> 1) * 32 + 8 * (fr >> 2) + 4 * (m & 1) + (fr & 3)) * 128 + cx; }
;     if (prefetched) {
;         if (Epi::STAGED) asm volatile("s_waitcnt vmcnt(8)" ::: "memory");
;         else asm volatile("s_waitcnt vmcnt(0)" ::: "memory");
;     } else {
;         GLDS_STAGE(0, pA, pB, 0);
;         asm volatile("s_waitcnt vmcnt(0)" ::: "memory");
; template <class Epi>
; __device__ __forceinline__ void gemm_phase(const bf16_t* A, const bf16_t* Bt, int M, int N, int K, const Epi& epi, char* smem) {
;     ...
;     for (int i = blockIdx.x; i < ntiles; i += G) {
;         const int j = i + G; const bool nv = j < ntiles;
;         gemm_tile(A, Bt, K, (i / nN) << 7, (i % nN) << 7, epi, smem, pre, nv, (j / nN) << 7, (j % nN) << 7);
.LBB0_718:
	s_and_b32 s8, s24, 7
	s_lshl_b32 s8, s8, 3
	s_bfe_u32 s9, s24, 0x30006
	s_or_b32 s8, s8, s9
	s_lshr_b32 s9, s24, 10
	s_lshl_b32 s9, s9, 6
	s_or_b32 s8, s8, s9
	s_lshl_b32 s8, s8, 4
	s_bfe_u32 s9, s24, 0x30003
	s_or_b32 s8, s8, s9
	s_bfe_u32 s9, s24, 0x10009
	s_lshl_b32 s9, s9, 3
	s_or_b32 s9, s8, s9
	s_ashr_i32 s0, s9, 31
	s_lshr_b32 s0, s0, 28
	s_add_i32 s0, s9, s0
	s_lshl_b32 s1, s0, 3
	s_and_b32 s0, s0, 0x1fffff0
	s_sub_i32 s0, s9, s0
	s_and_b32 s6, s1, 0xffffff80
	s_lshl_b32 s8, s0, 7
	s_ashr_i32 s7, s6, 31
	s_ashr_i32 s9, s8, 31
	s_lshl_b64 s[0:1], s[6:7], 11
	s_lshl_b64 s[10:11], s[8:9], 11
	s_mov_b64 s[14:15], -1
	s_and_b64 vcc, exec, s[12:13]
	s_cbranch_vccnz .LBB0_720
	v_readlane_b32 s7, v245, 53
	s_add_u32 s12, s7, s0
	v_readlane_b32 s7, v245, 54
	s_addc_u32 s13, s7, s1
	s_add_u32 s14, s3, s10
	v_readfirstlane_b32 s7, v149
	s_addc_u32 s15, s20, s11
	s_mov_b32 m0, s7
	v_readfirstlane_b32 s7, v163
	global_load_lds_dwordx4 v174, s[12:13]
	v_lshl_add_u64 v[0:1], v[84:85], 1, s[14:15]
	s_mov_b32 m0, s7
	v_readfirstlane_b32 s7, v164
	global_load_lds_dwordx4 v[0:1], off
	s_mov_b32 m0, s7
	v_readfirstlane_b32 s7, v165
	global_load_lds_dwordx4 v175, s[12:13]
	v_lshl_add_u64 v[0:1], v[86:87], 1, s[14:15]
	s_mov_b32 m0, s7
	v_readfirstlane_b32 s7, v166
	global_load_lds_dwordx4 v[0:1], off
	s_mov_b32 m0, s7
	v_readfirstlane_b32 s7, v170
	global_load_lds_dwordx4 v176, s[12:13]
	v_lshl_add_u64 v[0:1], v[88:89], 1, s[14:15]
	s_mov_b32 m0, s7
	v_readfirstlane_b32 s7, v171
	global_load_lds_dwordx4 v[0:1], off
	s_mov_b32 m0, s7
	v_readfirstlane_b32 s7, v172
	global_load_lds_dwordx4 v177, s[12:13]
	v_lshl_add_u64 v[0:1], v[90:91], 1, s[14:15]
	s_mov_b32 m0, s7
	s_mov_b64 s[14:15], 0
	global_load_lds_dwordx4 v[0:1], off
	s_waitcnt vmcnt(0)

; __device__ __forceinline__ f32x4 mfma16(bf16x8 a, bf16x8 b, f32x4 c) { return __builtin_amdgcn_mfma_f32_16x16x32_bf16(a, b, c, 0, 0, 0); }
; template <class Epi>
; __device__ __forceinline__ void gemm_tile(const bf16_t* __restrict__ A, const bf16_t* __restrict__ Bt, int K, int row0, int col0, const Epi& epi, char* smem,
;                                           bool prefetched, bool nvalid, int nrow0, int ncol0) {
;     ...
; #pragma unroll
;         for (int ks = 0; ks < 2; ++ks) {
;             bf16x8 a[4], b[4];
; #pragma unroll
;             for (int m = 0; m < 4; ++m) a[m] = *(const bf16x8*)(cb + offA[m][ks]);
; #pragma unroll
;             for (int n = 0; n < 4; ++n) b[n] = *(const bf16x8*)(cb + offB[n][ks]);
; #pragma unroll
;             for (int m = 0; m < 4; ++m)
; #pragma unroll
;                 for (int n = 0; n < 4; ++n) acc[m][n] = mfma16(b[n], a[m], acc[m][n]);
;         }
;         asm volatile("s_waitcnt vmcnt(0)" ::: "memory");
;         __syncthreads();
;     }
;     if (nvalid) { const bf16_t* qA = A + (size_t)nrow0 * K; const bf16_t* qB = Bt + (size_t)ncol0 * K; GLDS_STAGE(0, qA, qB, 0); }
; template <class Epi>
; __device__ __forceinline__ void gemm_phase(const bf16_t* A, const bf16_t* Bt, int M, int N, int K, const Epi& epi, char* smem) {
;     ...
;     for (int i = blockIdx.x; i < ntiles; i += G) {
;         const int j = i + G; const bool nv = j < ntiles;
;         gemm_tile(A, Bt, K, (i / nN) << 7, (i % nN) << 7, epi, smem, pre, nv, (j / nN) << 7, (j % nN) << 7);
.Lgk_tail_723:
	v_mfma_f32_16x16x32_bf16 v[32:35], v[80:83], v[246:249], v[32:35]
	v_mfma_f32_16x16x32_bf16 v[36:39], v[128:131], v[246:249], v[36:39]
	v_mfma_f32_16x16x32_bf16 v[40:43], v[180:183], v[246:249], v[40:43]
	v_mfma_f32_16x16x32_bf16 v[44:47], v[184:187], v[246:249], v[44:47]
	v_mfma_f32_16x16x32_bf16 v[48:51], v[80:83], v[250:253], v[48:51]
	v_mfma_f32_16x16x32_bf16 v[52:55], v[128:131], v[250:253], v[52:55]
	v_mfma_f32_16x16x32_bf16 v[56:59], v[180:183], v[250:253], v[56:59]
	v_mfma_f32_16x16x32_bf16 v[60:63], v[184:187], v[250:253], v[60:63]
	ds_read_b128 v[64:67], v143 offset:49152
	ds_read_b128 v[68:71], v137 offset:32768
	ds_read_b128 v[72:75], v143 offset:49664
	ds_read_b128 v[76:79], v143 offset:53248
	ds_read_b128 v[80:83], v143 offset:53760
	s_add_i32 s24, s24, s58
	s_waitcnt lgkmcnt(3)
	v_mfma_f32_16x16x32_bf16 v[0:3], v[64:67], v[68:71], v[0:3]
	s_cmpk_gt_i32 s24, 0xfff
	s_cselect_b64 s[10:11], -1, 0
	s_cmpk_lt_i32 s24, 0x1000
	s_waitcnt lgkmcnt(2)
	v_mfma_f32_16x16x32_bf16 v[4:7], v[72:75], v[68:71], v[4:7]
	ds_read_b128 v[188:191], v142 offset:49152
	ds_read_b128 v[192:195], v142 offset:53760
	s_waitcnt lgkmcnt(3)
	v_mfma_f32_16x16x32_bf16 v[8:11], v[76:79], v[68:71], v[8:11]
	s_waitcnt lgkmcnt(2)
	v_mfma_f32_16x16x32_bf16 v[12:15], v[80:83], v[68:71], v[12:15]
	ds_read_b128 v[68:71], v137 offset:34816
	s_waitcnt lgkmcnt(0)
	v_mfma_f32_16x16x32_bf16 v[16:19], v[64:67], v[68:71], v[16:19]
	v_mfma_f32_16x16x32_bf16 v[20:23], v[72:75], v[68:71], v[20:23]
	v_mfma_f32_16x16x32_bf16 v[24:27], v[76:79], v[68:71], v[24:27]
	v_mfma_f32_16x16x32_bf16 v[28:31], v[80:83], v[68:71], v[28:31]
	ds_read_b128 v[68:71], v137 offset:36864
	s_waitcnt lgkmcnt(0)
	v_mfma_f32_16x16x32_bf16 v[128:131], v[64:67], v[68:71], v[32:35]
	s_nop 2
	ds_read_b128 v[32:35], v137 offset:38912
	v_mfma_f32_16x16x32_bf16 v[180:183], v[72:75], v[68:71], v[36:39]
	v_mfma_f32_16x16x32_bf16 v[184:187], v[76:79], v[68:71], v[40:43]
	v_mfma_f32_16x16x32_bf16 v[68:71], v[80:83], v[68:71], v[44:47]
	s_waitcnt lgkmcnt(0)
	v_mfma_f32_16x16x32_bf16 v[64:67], v[64:67], v[32:35], v[48:51]
	v_mfma_f32_16x16x32_bf16 v[72:75], v[72:75], v[32:35], v[52:55]
	v_mfma_f32_16x16x32_bf16 v[76:79], v[76:79], v[32:35], v[56:59]
	v_mfma_f32_16x16x32_bf16 v[80:83], v[80:83], v[32:35], v[60:63]
	ds_read_b128 v[32:35], v141 offset:32768
	s_waitcnt lgkmcnt(0)
	v_mfma_f32_16x16x32_bf16 v[56:59], v[188:191], v[32:35], v[0:3]
	s_nop 2
	ds_read_b128 v[0:3], v142 offset:49664
	s_waitcnt lgkmcnt(0)
	v_mfma_f32_16x16x32_bf16 v[60:63], v[0:3], v[32:35], v[4:7]
	s_nop 2
	ds_read_b128 v[4:7], v142 offset:53248
	s_waitcnt lgkmcnt(0)
	v_mfma_f32_16x16x32_bf16 v[48:51], v[4:7], v[32:35], v[8:11]
	s_nop 2
	ds_read_b128 v[8:11], v141 offset:34816
	v_mfma_f32_16x16x32_bf16 v[52:55], v[192:195], v[32:35], v[12:15]
	s_waitcnt lgkmcnt(0)
	v_mfma_f32_16x16x32_bf16 v[40:43], v[188:191], v[8:11], v[16:19]
	v_mfma_f32_16x16x32_bf16 v[44:47], v[0:3], v[8:11], v[20:23]
	v_mfma_f32_16x16x32_bf16 v[32:35], v[4:7], v[8:11], v[24:27]
	v_mfma_f32_16x16x32_bf16 v[36:39], v[192:195], v[8:11], v[28:31]
	ds_read_b128 v[8:11], v141 offset:36864
	s_waitcnt lgkmcnt(0)
	v_mfma_f32_16x16x32_bf16 v[20:23], v[192:195], v[8:11], v[68:71]
	s_nop 2
	ds_read_b128 v[68:71], v141 offset:38912
	s_waitcnt vmcnt(0)
	v_mfma_f32_16x16x32_bf16 v[24:27], v[188:191], v[8:11], v[128:131]
	s_waitcnt lgkmcnt(0)
	s_barrier
	v_mfma_f32_16x16x32_bf16 v[28:31], v[0:3], v[8:11], v[180:183]
	v_mfma_f32_16x16x32_bf16 v[16:19], v[4:7], v[8:11], v[184:187]
	v_mfma_f32_16x16x32_bf16 v[8:11], v[188:191], v[68:71], v[64:67]
	v_mfma_f32_16x16x32_bf16 v[12:15], v[0:3], v[68:71], v[72:75]
	v_mfma_f32_16x16x32_bf16 v[0:3], v[4:7], v[68:71], v[76:79]
	v_mfma_f32_16x16x32_bf16 v[4:7], v[192:195], v[68:71], v[80:83]
	s_cbranch_scc0 .LBB0_726
	s_and_b32 s12, s24, 7
	s_lshl_b32 s12, s12, 3
	s_bfe_u32 s13, s24, 0x30006
	s_or_b32 s12, s12, s13
	s_lshr_b32 s13, s24, 10
	s_lshl_b32 s13, s13, 6
	s_or_b32 s12, s12, s13
	s_lshl_b32 s12, s12, 4
	s_bfe_u32 s13, s24, 0x30003
	s_or_b32 s12, s12, s13
	s_bfe_u32 s13, s24, 0x10009
	s_lshl_b32 s13, s13, 3
	s_or_b32 s13, s12, s13
	s_ashr_i32 s0, s13, 31
	s_lshr_b32 s0, s0, 28
	s_add_i32 s1, s13, s0
	s_lshl_b32 s0, s1, 3
	s_and_b32 s1, s1, 0x1fffff0
	s_and_b32 s0, s0, 0xffffff80
	s_sub_i32 s1, s13, s1
	s_lshl_b32 s12, s1, 7
	s_ashr_i32 s1, s0, 31
	s_lshl_b64 s[0:1], s[0:1], 11
	v_readlane_b32 s7, v245, 53
	s_add_u32 s0, s7, s0
	v_readlane_b32 s7, v245, 54
	s_addc_u32 s1, s7, s1
	s_ashr_i32 s13, s12, 31
	s_lshl_b64 s[12:13], s[12:13], 11
	s_add_u32 s12, s3, s12
	v_readfirstlane_b32 s7, v149
	s_addc_u32 s13, s20, s13
	s_mov_b32 m0, s7
	v_readfirstlane_b32 s7, v163
	global_load_lds_dwordx4 v174, s[0:1]
	v_lshl_add_u64 v[64:65], v[84:85], 1, s[12:13]
	s_mov_b32 m0, s7
	v_readfirstlane_b32 s7, v164
	global_load_lds_dwordx4 v[64:65], off
	s_mov_b32 m0, s7
	v_readfirstlane_b32 s7, v165
	global_load_lds_dwordx4 v175, s[0:1]
	v_lshl_add_u64 v[64:65], v[86:87], 1, s[12:13]
	s_mov_b32 m0, s7
	v_readfirstlane_b32 s7, v166
	global_load_lds_dwordx4 v[64:65], off
	s_mov_b32 m0, s7
	v_readfirstlane_b32 s7, v170
	global_load_lds_dwordx4 v176, s[0:1]
	v_lshl_add_u64 v[64:65], v[88:89], 1, s[12:13]
	s_mov_b32 m0, s7
	v_readfirstlane_b32 s7, v171
	global_load_lds_dwordx4 v[64:65], off
	s_mov_b32 m0, s7
	v_lshl_add_u64 v[64:65], v[90:91], 1, s[12:13]
	global_load_lds_dwordx4 v177, s[0:1]
	v_readfirstlane_b32 s0, v172
	s_mov_b32 m0, s0
	s_nop 0
	global_load_lds_dwordx4 v[64:65], off

; template <class Epi>
; __device__ __forceinline__ void gemm_tile(const bf16_t* __restrict__ A, const bf16_t* __restrict__ Bt, int K, int row0, int col0, const Epi& epi, char* smem,
;                                           bool prefetched, bool nvalid, int nrow0, int ncol0) {
;     ...
;     const bf16_t* pA = A + (size_t)row0 * K;
;     const bf16_t* pB = Bt + (size_t)col0 * K;
;     ...
;     int offA[4][2], offB[4][2];
; #pragma unroll
;     for (int m = 0; m < 4; ++m)
; #pragma unroll
;         for (int ks = 0; ks < 2; ++ks) { const int cx = ((ks * 4 + fq) ^ ((fr >> 1) & 7)) * 16;
;             offA[m][ks] = (wr * 64 + m * 16 + fr) * 128 + cx;
;             offB[m][ks] = TILE_B + (wc * 64 + (m >> 1) * 32 + 8 * (fr >> 2) + 4 * (m & 1) + (fr & 3)) * 128 + cx; }
;     if (prefetched) {
;         if (Epi::STAGED) asm volatile("s_waitcnt vmcnt(8)" ::: "memory");
;         else asm volatile("s_waitcnt vmcnt(0)" ::: "memory");
;     } else {
;         GLDS_STAGE(0, pA, pB, 0);
;         asm volatile("s_waitcnt vmcnt(0)" ::: "memory");
; template <class E1, class E2>
; __device__ __forceinline__ void gemm_phase2(const bf16_t* A1, const bf16_t* B1, int M1, int N1, const E1& e1,
;                                             const bf16_t* A2, const bf16_t* B2, int M2, int N2, const E2& e2, int K, char* smem) {
;     ...
;     for (int i = (blockIdx.x + (G >> 1)) % G; i < nt2; i += G) {
;         const int j = i + G; const bool nv = j < nt2;
;         gemm_tile(A2, B2, K, (i % nM2) << 7, (i / nM2) << 7, e2, smem, pre, nv, (j % nM2) << 7, (j / nM2) << 7);
.LBB0_761:
	v_readlane_b32 s2, v245, 59
	s_nop 0
	s_and_b32 s0, s2, 7
	s_lshl_b32 s0, s0, 3
	s_bfe_u32 s1, s2, 0x30003
	s_or_b32 s0, s0, s1
	s_and_b32 s2, s2, 0xffffffc0
	s_or_b32 s2, s2, s0
	s_ashr_i32 s0, s2, 31
	s_lshr_b32 s0, s0, 29
	s_add_i32 s0, s2, s0
	s_and_b32 s1, s0, 0x1fffff8
	s_sub_i32 s1, s2, s1
	s_lshl_b32 s0, s0, 4
	s_lshl_b32 s2, s1, 7
	s_and_b32 s0, s0, 0xffffff80
	s_ashr_i32 s3, s2, 31
	s_ashr_i32 s1, s0, 31
	s_lshl_b64 s[6:7], s[2:3], 11
	s_lshl_b64 s[8:9], s[0:1], 11
	s_mov_b64 s[12:13], -1
	s_and_b64 vcc, exec, s[10:11]
	s_cbranch_vccnz .LBB0_763
	s_add_u32 s10, s14, s6
	s_addc_u32 s11, s15, s7
	v_readlane_b32 s1, v245, 53
	s_add_u32 s12, s1, s8
	v_readlane_b32 s1, v245, 54
	s_addc_u32 s13, s1, s9
	v_readfirstlane_b32 s1, v149
	s_mov_b32 m0, s1
	v_readfirstlane_b32 s1, v132
	global_load_lds_dwordx4 v144, s[10:11]
	v_lshl_add_u64 v[0:1], v[64:65], 1, s[12:13]
	s_mov_b32 m0, s1
	v_readfirstlane_b32 s1, v133
	global_load_lds_dwordx4 v[0:1], off
	s_mov_b32 m0, s1
	v_readfirstlane_b32 s1, v134
	global_load_lds_dwordx4 v145, s[10:11]
	v_lshl_add_u64 v[0:1], v[66:67], 1, s[12:13]
	s_mov_b32 m0, s1
	v_readfirstlane_b32 s1, v135
	global_load_lds_dwordx4 v[0:1], off
	s_mov_b32 m0, s1
	v_readfirstlane_b32 s1, v136
	global_load_lds_dwordx4 v162, s[10:11]
	v_lshl_add_u64 v[0:1], v[68:69], 1, s[12:13]
	s_mov_b32 m0, s1
	v_readfirstlane_b32 s1, v137
	global_load_lds_dwordx4 v[0:1], off
	s_mov_b32 m0, s1
	v_readfirstlane_b32 s1, v141
	global_load_lds_dwordx4 v163, s[10:11]
	v_lshl_add_u64 v[0:1], v[70:71], 1, s[12:13]
	s_mov_b32 m0, s1
	s_mov_b64 s[12:13], 0
	global_load_lds_dwordx4 v[0:1], off
	s_waitcnt vmcnt(0)

; __device__ __forceinline__ f32x4 mfma16(bf16x8 a, bf16x8 b, f32x4 c) { return __builtin_amdgcn_mfma_f32_16x16x32_bf16(a, b, c, 0, 0, 0); }
; template <class Epi>
; __device__ __forceinline__ void gemm_tile(const bf16_t* __restrict__ A, const bf16_t* __restrict__ Bt, int K, int row0, int col0, const Epi& epi, char* smem,
;                                           bool prefetched, bool nvalid, int nrow0, int ncol0) {
;     ...
; #pragma unroll
;         for (int ks = 0; ks < 2; ++ks) {
;             bf16x8 a[4], b[4];
; #pragma unroll
;             for (int m = 0; m < 4; ++m) a[m] = *(const bf16x8*)(cb + offA[m][ks]);
; #pragma unroll
;             for (int n = 0; n < 4; ++n) b[n] = *(const bf16x8*)(cb + offB[n][ks]);
; #pragma unroll
;             for (int m = 0; m < 4; ++m)
; #pragma unroll
;                 for (int n = 0; n < 4; ++n) acc[m][n] = mfma16(b[n], a[m], acc[m][n]);
;         }
;         asm volatile("s_waitcnt vmcnt(0)" ::: "memory");
;         __syncthreads();
;     }
;     if (nvalid) { const bf16_t* qA = A + (size_t)nrow0 * K; const bf16_t* qB = Bt + (size_t)ncol0 * K; GLDS_STAGE(0, qA, qB, 0); }
; template <class E1, class E2>
; __device__ __forceinline__ void gemm_phase2(const bf16_t* A1, const bf16_t* B1, int M1, int N1, const E1& e1,
;                                             const bf16_t* A2, const bf16_t* B2, int M2, int N2, const E2& e2, int K, char* smem) {
;     ...
;     for (int i = (blockIdx.x + (G >> 1)) % G; i < nt2; i += G) {
;         const int j = i + G; const bool nv = j < nt2;
;         gemm_tile(A2, B2, K, (i % nM2) << 7, (i / nM2) << 7, e2, smem, pre, nv, (j % nM2) << 7, (j / nM2) << 7);
.Lgk_tail_766:
	v_mfma_f32_16x16x32_bf16 v[32:35], v[174:177], v[198:201], v[32:35]
	v_mfma_f32_16x16x32_bf16 v[36:39], v[178:181], v[198:201], v[36:39]
	v_mfma_f32_16x16x32_bf16 v[40:43], v[182:185], v[198:201], v[40:43]
	v_mfma_f32_16x16x32_bf16 v[44:47], v[186:189], v[198:201], v[44:47]
	v_mfma_f32_16x16x32_bf16 v[48:51], v[174:177], v[246:249], v[48:51]
	v_mfma_f32_16x16x32_bf16 v[52:55], v[178:181], v[246:249], v[52:55]
	v_mfma_f32_16x16x32_bf16 v[56:59], v[182:185], v[246:249], v[56:59]
	v_mfma_f32_16x16x32_bf16 v[60:63], v[186:189], v[246:249], v[60:63]
	ds_read_b128 v[106:109], v131 offset:49152
	ds_read_b128 v[118:121], v128 offset:32768
	ds_read_b128 v[122:125], v131 offset:49664
	ds_read_b128 v[170:173], v131 offset:53248
	ds_read_b128 v[174:177], v131 offset:53760
	v_readlane_b32 s1, v245, 59
	s_waitcnt lgkmcnt(3)
	v_mfma_f32_16x16x32_bf16 v[0:3], v[106:109], v[118:121], v[0:3]
	s_add_i32 s1, s1, s58
	s_cmpk_gt_i32 s1, 0x7ff
	s_cselect_b64 s[6:7], -1, 0
	s_waitcnt lgkmcnt(2)
	v_mfma_f32_16x16x32_bf16 v[4:7], v[122:125], v[118:121], v[4:7]
	ds_read_b128 v[190:193], v130 offset:49152
	s_cmpk_lt_i32 s1, 0x800
	v_writelane_b32 v245, s1, 59
	s_waitcnt lgkmcnt(2)
	v_mfma_f32_16x16x32_bf16 v[8:11], v[170:173], v[118:121], v[8:11]
	ds_read_b128 v[194:197], v130 offset:53248
	ds_read_b128 v[198:201], v130 offset:53760
	s_waitcnt lgkmcnt(3)
	v_mfma_f32_16x16x32_bf16 v[12:15], v[174:177], v[118:121], v[12:15]
	ds_read_b128 v[118:121], v128 offset:34816
	s_waitcnt lgkmcnt(0)
	v_mfma_f32_16x16x32_bf16 v[16:19], v[106:109], v[118:121], v[16:19]
	v_mfma_f32_16x16x32_bf16 v[20:23], v[122:125], v[118:121], v[20:23]
	v_mfma_f32_16x16x32_bf16 v[24:27], v[170:173], v[118:121], v[24:27]
	v_mfma_f32_16x16x32_bf16 v[28:31], v[174:177], v[118:121], v[28:31]
	ds_read_b128 v[118:121], v128 offset:36864
	s_waitcnt lgkmcnt(0)
	v_mfma_f32_16x16x32_bf16 v[178:181], v[106:109], v[118:121], v[32:35]
	s_nop 2
	ds_read_b128 v[32:35], v128 offset:38912
	v_mfma_f32_16x16x32_bf16 v[182:185], v[122:125], v[118:121], v[36:39]
	v_mfma_f32_16x16x32_bf16 v[186:189], v[170:173], v[118:121], v[40:43]
	v_mfma_f32_16x16x32_bf16 v[118:121], v[174:177], v[118:121], v[44:47]
	s_waitcnt lgkmcnt(0)
	v_mfma_f32_16x16x32_bf16 v[106:109], v[106:109], v[32:35], v[48:51]
	v_mfma_f32_16x16x32_bf16 v[122:125], v[122:125], v[32:35], v[52:55]
	v_mfma_f32_16x16x32_bf16 v[170:173], v[170:173], v[32:35], v[56:59]
	v_mfma_f32_16x16x32_bf16 v[174:177], v[174:177], v[32:35], v[60:63]
	ds_read_b128 v[32:35], v129 offset:32768
	s_waitcnt lgkmcnt(0)
	v_mfma_f32_16x16x32_bf16 v[56:59], v[190:193], v[32:35], v[0:3]
	s_nop 2
	ds_read_b128 v[0:3], v130 offset:49664
	s_waitcnt lgkmcnt(0)
	v_mfma_f32_16x16x32_bf16 v[60:63], v[0:3], v[32:35], v[4:7]
	s_nop 2
	ds_read_b128 v[4:7], v129 offset:34816
	v_mfma_f32_16x16x32_bf16 v[48:51], v[194:197], v[32:35], v[8:11]
	v_mfma_f32_16x16x32_bf16 v[52:55], v[198:201], v[32:35], v[12:15]
	s_nop 2
	ds_read_b128 v[12:15], v129 offset:38912
	s_waitcnt lgkmcnt(1)
	v_mfma_f32_16x16x32_bf16 v[44:47], v[190:193], v[4:7], v[16:19]
	v_mfma_f32_16x16x32_bf16 v[40:43], v[0:3], v[4:7], v[20:23]
	v_mfma_f32_16x16x32_bf16 v[36:39], v[194:197], v[4:7], v[24:27]
	v_mfma_f32_16x16x32_bf16 v[32:35], v[198:201], v[4:7], v[28:31]
	ds_read_b128 v[4:7], v129 offset:36864
	s_waitcnt vmcnt(0)
	s_waitcnt lgkmcnt(0)
	v_mfma_f32_16x16x32_bf16 v[28:31], v[190:193], v[4:7], v[178:181]
	s_barrier
	v_mfma_f32_16x16x32_bf16 v[24:27], v[0:3], v[4:7], v[182:185]
	v_mfma_f32_16x16x32_bf16 v[20:23], v[194:197], v[4:7], v[186:189]
	v_mfma_f32_16x16x32_bf16 v[16:19], v[198:201], v[4:7], v[118:121]
	v_mfma_f32_16x16x32_bf16 v[4:7], v[190:193], v[12:15], v[106:109]
	v_mfma_f32_16x16x32_bf16 v[8:11], v[0:3], v[12:15], v[122:125]
	v_mfma_f32_16x16x32_bf16 v[0:3], v[194:197], v[12:15], v[170:173]
	v_mfma_f32_16x16x32_bf16 v[12:15], v[198:201], v[12:15], v[174:177]
	s_cbranch_scc0 .LBB0_760
	v_readlane_b32 s9, v245, 59
	s_nop 0
	s_and_b32 s1, s9, 7
	s_lshl_b32 s1, s1, 3
	s_bfe_u32 s8, s9, 0x30003
	s_or_b32 s1, s1, s8
	s_and_b32 s9, s9, 0xffffffc0
	s_or_b32 s9, s9, s1
	s_ashr_i32 s1, s9, 31
	s_lshr_b32 s1, s1, 29
	s_add_i32 s1, s9, s1
	s_and_b32 s8, s1, 0x1fffff8
	s_sub_i32 s8, s9, s8
	s_lshl_b32 s8, s8, 7
	s_lshl_b32 s1, s1, 4
	s_ashr_i32 s9, s8, 31
	s_and_b32 s10, s1, 0xffffff80
	s_lshl_b64 s[8:9], s[8:9], 11
	s_add_u32 s8, s14, s8
	s_addc_u32 s9, s15, s9
	s_ashr_i32 s11, s10, 31
	s_lshl_b64 s[10:11], s[10:11], 11
	v_readlane_b32 s1, v245, 53
	s_add_u32 s10, s1, s10
	v_readlane_b32 s1, v245, 54
	s_addc_u32 s11, s1, s11
	v_readfirstlane_b32 s1, v149
	s_mov_b32 m0, s1
	v_readfirstlane_b32 s1, v132
	global_load_lds_dwordx4 v144, s[8:9]
	v_lshl_add_u64 v[106:107], v[64:65], 1, s[10:11]
	s_mov_b32 m0, s1
	v_readfirstlane_b32 s1, v133
	global_load_lds_dwordx4 v[106:107], off
	s_mov_b32 m0, s1
	v_readfirstlane_b32 s1, v134
	global_load_lds_dwordx4 v145, s[8:9]
	v_lshl_add_u64 v[106:107], v[66:67], 1, s[10:11]
	s_mov_b32 m0, s1
	v_readfirstlane_b32 s1, v135
	global_load_lds_dwordx4 v[106:107], off
	s_mov_b32 m0, s1
	v_readfirstlane_b32 s1, v136
	global_load_lds_dwordx4 v162, s[8:9]
	v_lshl_add_u64 v[106:107], v[68:69], 1, s[10:11]
	s_mov_b32 m0, s1
	v_readfirstlane_b32 s1, v137
	global_load_lds_dwordx4 v[106:107], off
	s_mov_b32 m0, s1
	v_readfirstlane_b32 s1, v141
	global_load_lds_dwordx4 v163, s[8:9]
	v_lshl_add_u64 v[106:107], v[70:71], 1, s[10:11]
	s_mov_b32 m0, s1
	s_nop 0
	global_load_lds_dwordx4 v[106:107], off
	s_branch .LBB0_760

; template <class Epi>
; __device__ __forceinline__ void gemm_tile(const bf16_t* __restrict__ A, const bf16_t* __restrict__ Bt, int K, int row0, int col0, const Epi& epi, char* smem,
;                                           bool prefetched, bool nvalid, int nrow0, int ncol0) {
;     ...
;     const bf16_t* pA = A + (size_t)row0 * K;
;     const bf16_t* pB = Bt + (size_t)col0 * K;
;     ...
;     int offA[4][2], offB[4][2];
; #pragma unroll
;     for (int m = 0; m < 4; ++m)
; #pragma unroll
;         for (int ks = 0; ks < 2; ++ks) { const int cx = ((ks * 4 + fq) ^ ((fr >> 1) & 7)) * 16;
;             offA[m][ks] = (wr * 64 + m * 16 + fr) * 128 + cx;
;             offB[m][ks] = TILE_B + (wc * 64 + (m >> 1) * 32 + 8 * (fr >> 2) + 4 * (m & 1) + (fr & 3)) * 128 + cx; }
;     if (prefetched) {
;         if (Epi::STAGED) asm volatile("s_waitcnt vmcnt(8)" ::: "memory");
;         else asm volatile("s_waitcnt vmcnt(0)" ::: "memory");
;     } else {
;         GLDS_STAGE(0, pA, pB, 0);
;         asm volatile("s_waitcnt vmcnt(0)" ::: "memory");
; template <class Epi>
; __device__ __forceinline__ void gemm_phase(const bf16_t* A, const bf16_t* Bt, int M, int N, int K, const Epi& epi, char* smem) {
;     ...
;     for (int i = blockIdx.x; i < ntiles; i += G) {
;         const int j = i + G; const bool nv = j < ntiles;
;         gemm_tile(A, Bt, K, (i / nN) << 7, (i % nN) << 7, epi, smem, pre, nv, (j / nN) << 7, (j % nN) << 7);
.LBB0_993:
	s_and_b32 s2, s16, 7
	s_lshl_b32 s2, s2, 3
	s_bfe_u32 s3, s16, 0x30006
	s_or_b32 s2, s2, s3
	s_lshr_b32 s3, s16, 11
	s_lshl_b32 s3, s3, 6
	s_or_b32 s2, s2, s3
	s_lshl_b32 s2, s2, 5
	s_bfe_u32 s3, s16, 0x30003
	s_or_b32 s2, s2, s3
	s_bfe_u32 s3, s16, 0x20009
	s_lshl_b32 s3, s3, 3
	s_or_b32 s3, s2, s3
	s_ashr_i32 s0, s3, 31
	s_lshr_b32 s0, s0, 27
	s_add_i32 s1, s3, s0
	s_lshl_b32 s0, s1, 2
	s_and_b32 s1, s1, 0x1ffffe0
	s_sub_i32 s1, s3, s1
	s_and_b32 s0, s0, 0xffffff80
	s_lshl_b32 s2, s1, 7
	s_ashr_i32 s1, s0, 31
	s_ashr_i32 s3, s2, 31
	s_lshl_b64 s[6:7], s[0:1], 11
	s_lshl_b64 s[8:9], s[2:3], 11
	s_mov_b64 s[12:13], -1
	s_and_b64 vcc, exec, s[10:11]
	s_cbranch_vccnz .LBB0_995
	v_readlane_b32 s10, v245, 53
	s_add_u32 s10, s10, s6
	v_readlane_b32 s11, v245, 54
	s_addc_u32 s11, s11, s7
	s_add_u32 s12, s14, s8
	v_readfirstlane_b32 s17, v149
	s_addc_u32 s13, s15, s9
	s_mov_b32 m0, s17
	v_readfirstlane_b32 s17, v134
	global_load_lds_dwordx4 v143, s[10:11]
	v_lshl_add_u64 v[0:1], v[64:65], 1, s[12:13]
	s_mov_b32 m0, s17
	v_readfirstlane_b32 s17, v135
	global_load_lds_dwordx4 v[0:1], off
	s_mov_b32 m0, s17
	v_readfirstlane_b32 s17, v136
	global_load_lds_dwordx4 v144, s[10:11]
	v_lshl_add_u64 v[0:1], v[66:67], 1, s[12:13]
	s_mov_b32 m0, s17
	v_readfirstlane_b32 s17, v137
	global_load_lds_dwordx4 v[0:1], off
	s_mov_b32 m0, s17
	v_readfirstlane_b32 s17, v138
	global_load_lds_dwordx4 v145, s[10:11]
	v_lshl_add_u64 v[0:1], v[68:69], 1, s[12:13]
	s_mov_b32 m0, s17
	v_readfirstlane_b32 s17, v139
	global_load_lds_dwordx4 v[0:1], off
	s_mov_b32 m0, s17
	v_lshl_add_u64 v[0:1], v[70:71], 1, s[12:13]
	global_load_lds_dwordx4 v157, s[10:11]
	v_readfirstlane_b32 s10, v140
	s_mov_b32 m0, s10
	s_mov_b64 s[12:13], 0
	global_load_lds_dwordx4 v[0:1], off
	s_waitcnt vmcnt(0)

; __device__ __forceinline__ f32x4 mfma16(bf16x8 a, bf16x8 b, f32x4 c) { return __builtin_amdgcn_mfma_f32_16x16x32_bf16(a, b, c, 0, 0, 0); }
; template <class Epi>
; __device__ __forceinline__ void gemm_tile(const bf16_t* __restrict__ A, const bf16_t* __restrict__ Bt, int K, int row0, int col0, const Epi& epi, char* smem,
;                                           bool prefetched, bool nvalid, int nrow0, int ncol0) {
;     ...
; #pragma unroll
;         for (int ks = 0; ks < 2; ++ks) {
;             bf16x8 a[4], b[4];
; #pragma unroll
;             for (int m = 0; m < 4; ++m) a[m] = *(const bf16x8*)(cb + offA[m][ks]);
; #pragma unroll
;             for (int n = 0; n < 4; ++n) b[n] = *(const bf16x8*)(cb + offB[n][ks]);
; #pragma unroll
;             for (int m = 0; m < 4; ++m)
; #pragma unroll
;                 for (int n = 0; n < 4; ++n) acc[m][n] = mfma16(b[n], a[m], acc[m][n]);
;         }
;         asm volatile("s_waitcnt vmcnt(0)" ::: "memory");
;         __syncthreads();
;     }
;     if (nvalid) { const bf16_t* qA = A + (size_t)nrow0 * K; const bf16_t* qB = Bt + (size_t)ncol0 * K; GLDS_STAGE(0, qA, qB, 0); }
; template <class Epi>
; __device__ __forceinline__ void gemm_phase(const bf16_t* A, const bf16_t* Bt, int M, int N, int K, const Epi& epi, char* smem) {
;     ...
;     for (int i = blockIdx.x; i < ntiles; i += G) {
;         const int j = i + G; const bool nv = j < ntiles;
;         gemm_tile(A, Bt, K, (i / nN) << 7, (i % nN) << 7, epi, smem, pre, nv, (j / nN) << 7, (j % nN) << 7);
.Lgk_tail_998:
	v_mfma_f32_16x16x32_bf16 v[32:35], v[168:171], v[246:249], v[32:35]
	v_mfma_f32_16x16x32_bf16 v[36:39], v[172:175], v[246:249], v[36:39]
	v_mfma_f32_16x16x32_bf16 v[40:43], v[176:179], v[246:249], v[40:43]
	v_mfma_f32_16x16x32_bf16 v[44:47], v[180:183], v[246:249], v[44:47]
	v_mfma_f32_16x16x32_bf16 v[48:51], v[168:171], v[250:253], v[48:51]
	v_mfma_f32_16x16x32_bf16 v[52:55], v[172:175], v[250:253], v[52:55]
	v_mfma_f32_16x16x32_bf16 v[56:59], v[176:179], v[250:253], v[56:59]
	v_mfma_f32_16x16x32_bf16 v[60:63], v[180:183], v[250:253], v[60:63]
	ds_read_b128 v[106:109], v133 offset:49152
	ds_read_b128 v[118:121], v130 offset:32768
	ds_read_b128 v[122:125], v133 offset:49664
	ds_read_b128 v[158:161], v133 offset:53248
	ds_read_b128 v[168:171], v133 offset:53760
	s_add_i32 s16, s16, s58
	s_waitcnt lgkmcnt(3)
	v_mfma_f32_16x16x32_bf16 v[0:3], v[106:109], v[118:121], v[0:3]
	s_cmpk_gt_i32 s16, 0x1fff
	s_cselect_b64 s[6:7], -1, 0
	s_cmpk_lt_i32 s16, 0x2000
	s_waitcnt lgkmcnt(2)
	v_mfma_f32_16x16x32_bf16 v[4:7], v[122:125], v[118:121], v[4:7]
	ds_read_b128 v[184:187], v132 offset:49152
	ds_read_b128 v[188:191], v132 offset:53760
	s_waitcnt lgkmcnt(3)
	v_mfma_f32_16x16x32_bf16 v[8:11], v[158:161], v[118:121], v[8:11]
	s_waitcnt lgkmcnt(2)
	v_mfma_f32_16x16x32_bf16 v[12:15], v[168:171], v[118:121], v[12:15]
	ds_read_b128 v[118:121], v130 offset:34816
	s_waitcnt lgkmcnt(0)
	v_mfma_f32_16x16x32_bf16 v[16:19], v[106:109], v[118:121], v[16:19]
	v_mfma_f32_16x16x32_bf16 v[20:23], v[122:125], v[118:121], v[20:23]
	v_mfma_f32_16x16x32_bf16 v[24:27], v[158:161], v[118:121], v[24:27]
	v_mfma_f32_16x16x32_bf16 v[28:31], v[168:171], v[118:121], v[28:31]
	ds_read_b128 v[118:121], v130 offset:36864
	s_waitcnt lgkmcnt(0)
	v_mfma_f32_16x16x32_bf16 v[172:175], v[106:109], v[118:121], v[32:35]
	s_nop 2
	ds_read_b128 v[32:35], v130 offset:38912
	v_mfma_f32_16x16x32_bf16 v[176:179], v[122:125], v[118:121], v[36:39]
	v_mfma_f32_16x16x32_bf16 v[180:183], v[158:161], v[118:121], v[40:43]
	v_mfma_f32_16x16x32_bf16 v[118:121], v[168:171], v[118:121], v[44:47]
	s_waitcnt lgkmcnt(0)
	v_mfma_f32_16x16x32_bf16 v[106:109], v[106:109], v[32:35], v[48:51]
	v_mfma_f32_16x16x32_bf16 v[122:125], v[122:125], v[32:35], v[52:55]
	v_mfma_f32_16x16x32_bf16 v[158:161], v[158:161], v[32:35], v[56:59]
	v_mfma_f32_16x16x32_bf16 v[168:171], v[168:171], v[32:35], v[60:63]
	ds_read_b128 v[32:35], v131 offset:32768
	s_waitcnt lgkmcnt(0)
	v_mfma_f32_16x16x32_bf16 v[56:59], v[184:187], v[32:35], v[0:3]
	s_nop 2
	ds_read_b128 v[0:3], v132 offset:49664
	s_waitcnt lgkmcnt(0)
	v_mfma_f32_16x16x32_bf16 v[60:63], v[0:3], v[32:35], v[4:7]
	s_nop 2
	ds_read_b128 v[4:7], v132 offset:53248
	s_waitcnt lgkmcnt(0)
	v_mfma_f32_16x16x32_bf16 v[48:51], v[4:7], v[32:35], v[8:11]
	s_nop 2
	ds_read_b128 v[8:11], v131 offset:34816
	v_mfma_f32_16x16x32_bf16 v[52:55], v[188:191], v[32:35], v[12:15]
	s_waitcnt lgkmcnt(0)
	v_mfma_f32_16x16x32_bf16 v[44:47], v[184:187], v[8:11], v[16:19]
	v_mfma_f32_16x16x32_bf16 v[40:43], v[0:3], v[8:11], v[20:23]
	v_mfma_f32_16x16x32_bf16 v[36:39], v[4:7], v[8:11], v[24:27]
	v_mfma_f32_16x16x32_bf16 v[32:35], v[188:191], v[8:11], v[28:31]
	ds_read_b128 v[8:11], v131 offset:36864
	s_waitcnt lgkmcnt(0)
	v_mfma_f32_16x16x32_bf16 v[16:19], v[188:191], v[8:11], v[118:121]
	s_nop 2
	ds_read_b128 v[118:121], v131 offset:38912
	s_waitcnt vmcnt(0)
	v_mfma_f32_16x16x32_bf16 v[28:31], v[184:187], v[8:11], v[172:175]
	s_waitcnt lgkmcnt(0)
	s_barrier
	v_mfma_f32_16x16x32_bf16 v[24:27], v[0:3], v[8:11], v[176:179]
	v_mfma_f32_16x16x32_bf16 v[20:23], v[4:7], v[8:11], v[180:183]
	v_mfma_f32_16x16x32_bf16 v[8:11], v[184:187], v[118:121], v[106:109]
	v_mfma_f32_16x16x32_bf16 v[12:15], v[0:3], v[118:121], v[122:125]
	v_mfma_f32_16x16x32_bf16 v[0:3], v[4:7], v[118:121], v[158:161]
	v_mfma_f32_16x16x32_bf16 v[4:7], v[188:191], v[118:121], v[168:171]
	s_cbranch_scc0 .LBB0_992
	s_and_b32 s10, s16, 7
	s_lshl_b32 s10, s10, 3
	s_bfe_u32 s11, s16, 0x30006
	s_or_b32 s10, s10, s11
	s_lshr_b32 s11, s16, 11
	s_lshl_b32 s11, s11, 6
	s_or_b32 s10, s10, s11
	s_lshl_b32 s10, s10, 5
	s_bfe_u32 s11, s16, 0x30003
	s_or_b32 s10, s10, s11
	s_bfe_u32 s11, s16, 0x20009
	s_lshl_b32 s11, s11, 3
	s_or_b32 s11, s10, s11
	s_ashr_i32 s8, s11, 31
	s_lshr_b32 s8, s8, 27
	s_add_i32 s9, s11, s8
	s_lshl_b32 s8, s9, 2
	s_and_b32 s9, s9, 0x1ffffe0
	s_and_b32 s8, s8, 0xffffff80
	s_sub_i32 s9, s11, s9
	s_lshl_b32 s10, s9, 7
	s_ashr_i32 s9, s8, 31
	s_lshl_b64 s[8:9], s[8:9], 11
	v_readlane_b32 s11, v245, 53
	s_add_u32 s8, s11, s8
	v_readlane_b32 s11, v245, 54
	s_addc_u32 s9, s11, s9
	s_ashr_i32 s11, s10, 31
	s_lshl_b64 s[10:11], s[10:11], 11
	s_add_u32 s10, s14, s10
	v_readfirstlane_b32 s12, v149
	s_addc_u32 s11, s15, s11
	s_mov_b32 m0, s12
	v_readfirstlane_b32 s12, v134
	global_load_lds_dwordx4 v143, s[8:9]
	v_lshl_add_u64 v[106:107], v[64:65], 1, s[10:11]
	s_mov_b32 m0, s12
	v_readfirstlane_b32 s12, v135
	global_load_lds_dwordx4 v[106:107], off
	s_mov_b32 m0, s12
	v_readfirstlane_b32 s12, v136
	global_load_lds_dwordx4 v144, s[8:9]
	v_lshl_add_u64 v[106:107], v[66:67], 1, s[10:11]
	s_mov_b32 m0, s12
	v_readfirstlane_b32 s12, v137
	global_load_lds_dwordx4 v[106:107], off
	s_mov_b32 m0, s12
	v_readfirstlane_b32 s12, v138
	global_load_lds_dwordx4 v145, s[8:9]
	v_lshl_add_u64 v[106:107], v[68:69], 1, s[10:11]
	s_mov_b32 m0, s12
	v_readfirstlane_b32 s12, v139
	global_load_lds_dwordx4 v[106:107], off
	s_mov_b32 m0, s12
	v_lshl_add_u64 v[106:107], v[70:71], 1, s[10:11]
	global_load_lds_dwordx4 v157, s[8:9]
	v_readfirstlane_b32 s8, v140
	s_mov_b32 m0, s8
	s_nop 0
	global_load_lds_dwordx4 v[106:107], off
	s_branch .LBB0_992
